# entry cooperative grid.sync() removed (census spin in the first XCD barrier already orders start-up)
# speedup vs baseline: 1.0199x; 1.0069x over previous
; #define LAS __attribute__((address_space(3)))
; __device__ __forceinline__ unsigned xb_add(unsigned* p, unsigned v) { return __hip_atomic_fetch_add(p, v, __ATOMIC_RELAXED, __HIP_MEMORY_SCOPE_AGENT); }
; __device__ __forceinline__ unsigned xb_xcc_id() { return (unsigned)__builtin_amdgcn_s_getreg((3 << 11) | 20) & 0xFu; }
; template <int ph>
; __device__ __forceinline__ void run_phase(const Args& args, LAS unsigned char* lds, const int G, const int bx, const bool fin = true) {
;     ...
;     case 0: if (PHSEL(0)) { PH_IDS
;         const float *x_prompt = INP(0), *x_sample = INP(1), *mem_prompt = INP(2), *decay_w2 = INP(18), *aaa_a2 = INP(20), *gate_g2 = INP(21), *lru_wr = INP(29), *lru_wi = INP(31);
;         LAS float* scr = (LAS float*)(lds + wave * 16384);
;         constexpr int I_WI = 16 * (2 * FF / 32), I_WO = (FF / 64) * 32, I_WIN = 16 * (PW / 32), I_SQ = 16 * 32;
;         constexpr int NIT = I_WI + I_WO + I_WIN + 5 * I_SQ;
;         for (int it = gw; it < NIT; it += ngw) {
;             int r = it;
;             if (r < I_WI) { transpose_item(INP(11), D, 2 * FF, WI, 1, scr, r, lane); continue; } r -= I_WI;
;             if (r < I_WO) { transpose_item(INP(12), FF, D, WO, 0, scr, r, lane); continue; } r -= I_WO;
; __global__ void __launch_bounds__(NTHR, 2) mega(Args args) {
;     extern __shared__ __attribute__((aligned(16))) unsigned char lds_raw[];
;     LAS unsigned char* lds = (LAS unsigned char*)lds_raw;
;     cg::grid_group grid = cg::this_grid();
;     const int G = gridDim.x, bx = blockIdx.x;
;     const int lo = args.ph_lo, hi = args.ph_hi;
;     unsigned* const bar = (unsigned*)args.ws;
;     volatile LAS unsigned* const bst = (volatile LAS unsigned*)(lds + 131072 + 64);
;     if (threadIdx.x < 2) bst[threadIdx.x] = 0u;
;     if (threadIdx.x == 0) (void)xb_add(&bar[XB_XCNT(xb_xcc_id())], 1u);
;     grid.sync();
.LBB0_15:
	s_load_dwordx16 s[16:31], s[0:1], 0x0
	s_cmp_lt_i32 s96, 1
	s_waitcnt lgkmcnt(0)
	v_writelane_b32 v229, s16, 0
	s_nop 1
	v_writelane_b32 v229, s17, 1
	v_writelane_b32 v229, s18, 2
	v_writelane_b32 v229, s19, 3
	v_writelane_b32 v229, s20, 4
	v_writelane_b32 v229, s21, 5
	v_writelane_b32 v229, s22, 6
	v_writelane_b32 v229, s23, 7
	v_writelane_b32 v229, s24, 8
	v_writelane_b32 v229, s25, 9
	v_writelane_b32 v229, s26, 10
	v_writelane_b32 v229, s27, 11
	v_writelane_b32 v229, s28, 12
	v_writelane_b32 v229, s29, 13
	v_writelane_b32 v229, s30, 14
	v_writelane_b32 v229, s31, 15
	s_load_dwordx16 s[16:31], s[0:1], 0x40
	s_waitcnt lgkmcnt(0)
	v_writelane_b32 v229, s16, 16
	s_nop 1
	v_writelane_b32 v229, s17, 17
	v_writelane_b32 v229, s18, 18
	v_writelane_b32 v229, s19, 19
	v_writelane_b32 v229, s20, 20
	v_writelane_b32 v229, s21, 21
	v_writelane_b32 v229, s22, 22
	v_writelane_b32 v229, s23, 23
	v_writelane_b32 v229, s24, 24
	v_writelane_b32 v229, s25, 25
	v_writelane_b32 v229, s26, 26
	v_writelane_b32 v229, s27, 27
	v_writelane_b32 v229, s28, 28
	v_writelane_b32 v229, s29, 29
	v_writelane_b32 v229, s30, 30
	v_writelane_b32 v229, s31, 31
	s_load_dwordx16 s[36:51], s[0:1], 0x80
	s_load_dwordx16 s[16:31], s[0:1], 0xc0
	s_barrier
	s_waitcnt lgkmcnt(0)
	v_writelane_b32 v229, s16, 32
	s_nop 1
	v_writelane_b32 v229, s17, 33
	v_writelane_b32 v229, s18, 34
	v_writelane_b32 v229, s19, 35
	v_writelane_b32 v229, s20, 36
	v_writelane_b32 v229, s21, 37
	v_writelane_b32 v229, s22, 38
	v_writelane_b32 v229, s23, 39
	v_writelane_b32 v229, s24, 40
	v_writelane_b32 v229, s25, 41
	v_writelane_b32 v229, s26, 42
	v_writelane_b32 v229, s27, 43
	v_writelane_b32 v229, s28, 44
	v_writelane_b32 v229, s29, 45
	v_writelane_b32 v229, s30, 46
	v_writelane_b32 v229, s31, 47
	s_load_dwordx16 s[4:19], s[0:1], 0x100
	s_cselect_b64 s[0:1], -1, 0
	s_cmp_gt_i32 s97, 0
	s_cselect_b64 s[2:3], -1, 0
	s_and_b64 s[0:1], s[0:1], s[2:3]
	s_waitcnt lgkmcnt(0)
	v_writelane_b32 v229, s4, 48
	s_andn2_b64 vcc, exec, s[0:1]
	s_nop 0
	v_writelane_b32 v229, s5, 49
	v_writelane_b32 v229, s6, 50
	v_writelane_b32 v229, s7, 51
	v_writelane_b32 v229, s8, 52
	v_writelane_b32 v229, s9, 53
	v_writelane_b32 v229, s10, 54
	v_writelane_b32 v229, s11, 55
	v_writelane_b32 v229, s12, 56
	v_writelane_b32 v229, s13, 57
	v_writelane_b32 v229, s14, 58
	v_writelane_b32 v229, s15, 59
	v_writelane_b32 v229, s16, 60
	v_writelane_b32 v229, s17, 61
	v_writelane_b32 v229, s18, 62
	v_writelane_b32 v229, s19, 63
	s_cbranch_vccnz .LBB0_143
	v_mov_b32_e32 v34, v202
	s_lshl_b32 s1, s81, 3
	v_readfirstlane_b32 s0, v34
	s_ashr_i32 s0, s0, 6
	s_add_i32 s8, s0, s1
	s_cmpk_gt_i32 s8, 0x28ff
	s_cbranch_scc1 .LBB0_61
	s_lshl_b32 s0, s0, 14
	v_bfe_u32 v35, v34, 5, 1
	v_lshlrev_b32_e32 v0, 2, v34
	s_add_i32 s0, s0, 0
	v_and_b32_e32 v32, 0x7c, v0
	v_mul_u32_u24_e32 v0, 0x84, v35
	v_add3_u32 v36, s0, v32, v0
	v_lshlrev_b32_e32 v0, 3, v34
	v_and_b32_e32 v0, 56, v0
	v_mul_u32_u24_e32 v4, 0x84, v0
	v_lshlrev_b32_e32 v0, 1, v0
	v_mov_b32_e32 v1, 0
	v_bfe_u32 v37, v34, 3, 3
	v_lshl_add_u64 v[16:17], s[34:35], 0, v[0:1]
	s_mov_b64 s[2:3], 0x2600000
	v_lshl_add_u64 v[2:3], v[16:17], 0, s[2:3]
	v_lshlrev_b32_e32 v0, 2, v37
	s_mov_b64 s[2:3], 0x2a00000
	v_add3_u32 v38, s0, v4, v0
	v_lshl_add_u64 v[4:5], v[16:17], 0, s[2:3]
	s_mov_b64 s[2:3], 0x2800000
	v_lshl_add_u64 v[6:7], v[16:17], 0, s[2:3]
	s_mov_b64 s[2:3], 0x2400000
	v_lshl_add_u64 v[8:9], v[16:17], 0, s[2:3]
	s_mov_b64 s[2:3], 0x2200000
	v_lshl_add_u64 v[10:11], v[16:17], 0, s[2:3]
	s_mov_b64 s[2:3], 0x1300000
	v_readlane_b32 s12, v229, 48
	v_lshl_add_u64 v[12:13], v[16:17], 0, s[2:3]
	s_mov_b64 s[2:3], 0xc00000
	v_readlane_b32 s13, v229, 49
	v_readlane_b32 s52, v229, 16
	s_lshl_b32 s0, s8, 6
	v_lshl_add_u64 v[14:15], v[16:17], 0, s[2:3]
	s_mov_b64 s[2:3], 0x100000
	v_mov_b32_e32 v33, v1
	v_readlane_b32 s14, v229, 50
	v_readlane_b32 s15, v229, 51
	v_readlane_b32 s16, v229, 52
	v_readlane_b32 s17, v229, 53
	v_readlane_b32 s18, v229, 54
	v_readlane_b32 s19, v229, 55
	v_readlane_b32 s20, v229, 56
	v_readlane_b32 s21, v229, 57
	v_readlane_b32 s22, v229, 58
	v_readlane_b32 s23, v229, 59
	v_readlane_b32 s24, v229, 60
	v_readlane_b32 s25, v229, 61
	v_readlane_b32 s26, v229, 62
	v_readlane_b32 s27, v229, 63
	v_readlane_b32 s53, v229, 17
	v_readlane_b32 s54, v229, 18
	v_readlane_b32 s55, v229, 19
	v_readlane_b32 s56, v229, 20
	v_readlane_b32 s57, v229, 21
	v_readlane_b32 s58, v229, 22
	v_readlane_b32 s59, v229, 23
	v_readlane_b32 s60, v229, 24
	v_readlane_b32 s61, v229, 25
	v_readlane_b32 s66, v229, 30
	v_readlane_b32 s67, v229, 31
	s_add_i32 s13, s0, 0x7fffea00
	s_lshl_b32 s0, s8, 1
	s_lshl_b32 s9, s33, 3
	s_mov_b32 s1, 0
	v_or_b32_e32 v39, 8, v37
	v_or_b32_e32 v40, 16, v37
	v_or_b32_e32 v41, 24, v37
	v_lshl_add_u64 v[16:17], v[16:17], 0, s[2:3]
	v_lshl_add_u64 v[18:19], s[24:25], 0, v[32:33]
	v_lshl_add_u64 v[20:21], s[22:23], 0, v[32:33]
	v_lshl_add_u64 v[22:23], s[20:21], 0, v[32:33]
	v_lshl_add_u64 v[24:25], s[18:19], 0, v[32:33]
	v_lshl_add_u64 v[26:27], s[16:17], 0, v[32:33]
	v_lshl_add_u64 v[28:29], s[66:67], 0, v[32:33]
	v_lshl_add_u64 v[30:31], s[60:61], 0, v[32:33]
	v_lshl_add_u64 v[32:33], s[58:59], 0, v[32:33]
	s_lshl_b32 s10, s8, 5
	s_lshl_b32 s11, s33, 8
	s_lshl_b32 s14, s33, 9
	s_add_i32 s15, s0, 0x1b200
	s_lshl_b32 s20, s33, 4
	s_mov_b32 s21, 0x105000
	s_mov_b32 s22, 0x113000
	s_mov_b32 s23, 0x122000
	s_mov_b32 s24, 0x130000
	s_mov_b32 s25, 0x13f000
	s_mov_b32 s26, 0x14d000
	s_mov_b32 s27, 0x15c000
	s_mov_b32 s28, 0x16a000
	s_mov_b32 s29, 0x179000
	s_mov_b32 s52, 0x187000
	s_mov_b32 s53, 0x196000
	s_mov_b32 s54, 0x1a4000
	s_mov_b32 s55, 0x1b3000
	s_mov_b32 s56, 0x1c1000
	v_add_u32_e32 v42, 0x400, v36
	v_add_u32_e32 v43, 0x800, v36
	v_add_u32_e32 v44, 0xc00, v36
	v_add_u32_e32 v45, 0x1000, v36
	v_add_u32_e32 v46, 0x1400, v36
	v_add_u32_e32 v47, 0x1800, v36
	v_add_u32_e32 v48, 0x1c00, v36
	s_movk_i32 s57, 0x5800
	v_readlane_b32 s62, v229, 26
	v_readlane_b32 s63, v229, 27
	v_readlane_b32 s64, v229, 28
	v_readlane_b32 s65, v229, 29
	s_branch .LBB0_20
